# GEMM K-loop rewritten as 4 phases of 32 MFMAs (8 barriers per 2 K-tiles instead of 16); LDS-DMA waits vmcnt(8) per phase; same MFMAs, same LDS ring
# speedup vs baseline: 1.0123x; 1.0110x over previous
.LBB0_919:
	s_add_i32 s42, s20, 2
	s_add_u32 s24, s18, 0x80
	s_addc_u32 s21, s19, 0
	s_add_i32 s43, 0, 0x10000
	v_add_u32_e32 v0, s43, v211
	s_waitcnt lgkmcnt(0)
	ds_read_b128 v[130:133], v0
	ds_read_b128 v[134:137], v0 offset:1024
	ds_read_b128 v[138:141], v0 offset:2048
	ds_read_b128 v[142:145], v0 offset:3072
	s_cmp_eq_u32 s66, s20
	s_cselect_b32 s20, s74, s24
	s_cselect_b32 s21, s75, s21
	s_cselect_b32 s25, s77, s39
	s_cselect_b32 s24, s76, s38
	s_add_i32 s44, 0, 0x14000
	v_add_u32_e32 v0, s44, v211
	v_lshl_add_u64 v[198:199], s[18:19], 0, v[184:185]
	s_add_i32 m0, s31, 0xc000
	ds_read_b128 v[232:235], v0
	ds_read_b128 v[236:239], v0 offset:1024
	ds_read_b128 v[240:243], v0 offset:2048
	ds_read_b128 v[244:247], v0 offset:3072
	global_load_lds_dwordx4 v[198:199], off
	v_lshl_add_u64 v[198:199], s[18:19], 0, v[182:183]
	s_add_i32 m0, s31, 0xe000
	s_nop 0
	global_load_lds_dwordx4 v[198:199], off
	ds_read_b128 v[146:149], v212
	ds_read_b128 v[150:153], v212 offset:1024
	ds_read_b128 v[154:157], v212 offset:2048
	ds_read_b128 v[158:161], v212 offset:3072
	ds_read_b128 v[186:189], v212 offset:4096
	ds_read_b128 v[190:193], v212 offset:5120
	s_waitcnt lgkmcnt(12)
	ds_read_b128 v[194:197], v212 offset:6144
	ds_read_b128 v[214:217], v212 offset:7168
	s_waitcnt vmcnt(8) lgkmcnt(0)
	s_barrier
	s_setprio 1
	v_mfma_f32_16x16x32_bf16 v[126:129], v[130:133], v[146:149], v[126:129]
	v_mfma_f32_16x16x32_bf16 v[122:125], v[138:141], v[146:149], v[122:125]
	v_mfma_f32_16x16x32_bf16 v[110:113], v[130:133], v[154:157], v[110:113]
	v_mfma_f32_16x16x32_bf16 v[106:109], v[138:141], v[154:157], v[106:109]
	v_mfma_f32_16x16x32_bf16 v[94:97], v[130:133], v[186:189], v[94:97]
	v_mfma_f32_16x16x32_bf16 v[90:93], v[138:141], v[186:189], v[90:93]
	v_mfma_f32_16x16x32_bf16 v[78:81], v[130:133], v[194:197], v[78:81]
	v_mfma_f32_16x16x32_bf16 v[74:77], v[138:141], v[194:197], v[74:77]
	v_mfma_f32_16x16x32_bf16 v[126:129], v[134:137], v[150:153], v[126:129]
	v_mfma_f32_16x16x32_bf16 v[122:125], v[142:145], v[150:153], v[122:125]
	v_mfma_f32_16x16x32_bf16 v[110:113], v[134:137], v[158:161], v[110:113]
	v_mfma_f32_16x16x32_bf16 v[106:109], v[142:145], v[158:161], v[106:109]
	v_mfma_f32_16x16x32_bf16 v[94:97], v[134:137], v[190:193], v[94:97]
	v_mfma_f32_16x16x32_bf16 v[90:93], v[142:145], v[190:193], v[90:93]
	v_mfma_f32_16x16x32_bf16 v[78:81], v[134:137], v[214:217], v[78:81]
	v_mfma_f32_16x16x32_bf16 v[74:77], v[142:145], v[214:217], v[74:77]
	v_mfma_f32_16x16x32_bf16 v[118:121], v[232:235], v[146:149], v[118:121]
	v_mfma_f32_16x16x32_bf16 v[114:117], v[240:243], v[146:149], v[114:117]
	v_mfma_f32_16x16x32_bf16 v[102:105], v[232:235], v[154:157], v[102:105]
	v_mfma_f32_16x16x32_bf16 v[98:101], v[240:243], v[154:157], v[98:101]
	v_mfma_f32_16x16x32_bf16 v[86:89], v[232:235], v[186:189], v[86:89]
	v_mfma_f32_16x16x32_bf16 v[82:85], v[240:243], v[186:189], v[82:85]
	v_mfma_f32_16x16x32_bf16 v[70:73], v[232:235], v[194:197], v[70:73]
	v_mfma_f32_16x16x32_bf16 v[66:69], v[240:243], v[194:197], v[66:69]
	v_mfma_f32_16x16x32_bf16 v[118:121], v[236:239], v[150:153], v[118:121]
	v_mfma_f32_16x16x32_bf16 v[114:117], v[244:247], v[150:153], v[114:117]
	v_mfma_f32_16x16x32_bf16 v[102:105], v[236:239], v[158:161], v[102:105]
	v_mfma_f32_16x16x32_bf16 v[98:101], v[244:247], v[158:161], v[98:101]
	v_mfma_f32_16x16x32_bf16 v[86:89], v[236:239], v[190:193], v[86:89]
	v_mfma_f32_16x16x32_bf16 v[82:85], v[244:247], v[190:193], v[82:85]
	v_mfma_f32_16x16x32_bf16 v[70:73], v[236:239], v[214:217], v[70:73]
	v_mfma_f32_16x16x32_bf16 v[66:69], v[244:247], v[214:217], v[66:69]
	s_setprio 0
	s_barrier
	ds_read_b128 v[146:149], v212 offset:16384
	ds_read_b128 v[150:153], v212 offset:17408
	ds_read_b128 v[154:157], v212 offset:18432
	ds_read_b128 v[158:161], v212 offset:19456
	ds_read_b128 v[186:189], v212 offset:20480
	ds_read_b128 v[190:193], v212 offset:21504
	ds_read_b128 v[194:197], v212 offset:22528
	ds_read_b128 v[214:217], v212 offset:23552
	s_add_i32 s43, s43, s30
	v_lshl_add_u64 v[198:199], s[24:25], 0, v[170:171]
	s_mov_b32 m0, s43
	v_lshl_add_u64 v[218:219], s[24:25], 0, v[174:175]
	global_load_lds_dwordx4 v[198:199], off
	s_add_i32 m0, s43, 0x2000
	s_nop 0
	global_load_lds_dwordx4 v[218:219], off
	s_mov_b32 m0, s31
	v_lshl_add_u64 v[248:249], s[20:21], 0, v[168:169]
	v_lshl_add_u64 v[250:251], s[20:21], 0, v[172:173]
	global_load_lds_dwordx4 v[248:249], off
	s_mov_b32 m0, s95
	s_nop 0
	global_load_lds_dwordx4 v[250:251], off
	s_add_u32 s24, s24, s60
	s_addc_u32 s25, s25, 0
	s_add_i32 s43, s44, s30
	v_lshl_add_u64 v[226:227], s[24:25], 0, v[170:171]
	s_mov_b32 m0, s43
	v_lshl_add_u64 v[228:229], s[24:25], 0, v[174:175]
	global_load_lds_dwordx4 v[226:227], off
	s_add_i32 m0, s43, 0x2000
	s_nop 0
	global_load_lds_dwordx4 v[228:229], off
	s_waitcnt vmcnt(8) lgkmcnt(0)
	s_barrier
	s_setprio 1
	v_mfma_f32_16x16x32_bf16 v[62:65], v[130:133], v[146:149], v[62:65]
	v_mfma_f32_16x16x32_bf16 v[58:61], v[138:141], v[146:149], v[58:61]
	v_mfma_f32_16x16x32_bf16 v[46:49], v[130:133], v[154:157], v[46:49]
	v_mfma_f32_16x16x32_bf16 v[42:45], v[138:141], v[154:157], v[42:45]
	v_mfma_f32_16x16x32_bf16 v[30:33], v[130:133], v[186:189], v[30:33]
	v_mfma_f32_16x16x32_bf16 v[26:29], v[138:141], v[186:189], v[26:29]
	v_mfma_f32_16x16x32_bf16 v[14:17], v[130:133], v[194:197], v[14:17]
	v_mfma_f32_16x16x32_bf16 v[10:13], v[138:141], v[194:197], v[10:13]
	v_mfma_f32_16x16x32_bf16 v[62:65], v[134:137], v[150:153], v[62:65]
	v_mfma_f32_16x16x32_bf16 v[58:61], v[142:145], v[150:153], v[58:61]
	v_mfma_f32_16x16x32_bf16 v[46:49], v[134:137], v[158:161], v[46:49]
	v_mfma_f32_16x16x32_bf16 v[42:45], v[142:145], v[158:161], v[42:45]
	v_mfma_f32_16x16x32_bf16 v[30:33], v[134:137], v[190:193], v[30:33]
	v_mfma_f32_16x16x32_bf16 v[26:29], v[142:145], v[190:193], v[26:29]
	v_mfma_f32_16x16x32_bf16 v[14:17], v[134:137], v[214:217], v[14:17]
	v_mfma_f32_16x16x32_bf16 v[10:13], v[142:145], v[214:217], v[10:13]
	v_mfma_f32_16x16x32_bf16 v[54:57], v[232:235], v[146:149], v[54:57]
	v_mfma_f32_16x16x32_bf16 v[50:53], v[240:243], v[146:149], v[50:53]
	v_mfma_f32_16x16x32_bf16 v[38:41], v[232:235], v[154:157], v[38:41]
	v_mfma_f32_16x16x32_bf16 v[34:37], v[240:243], v[154:157], v[34:37]
	v_mfma_f32_16x16x32_bf16 v[22:25], v[232:235], v[186:189], v[22:25]
	v_mfma_f32_16x16x32_bf16 v[18:21], v[240:243], v[186:189], v[18:21]
	v_mfma_f32_16x16x32_bf16 v[6:9], v[232:235], v[194:197], v[6:9]
	v_mfma_f32_16x16x32_bf16 v[2:5], v[240:243], v[194:197], v[2:5]
	v_mfma_f32_16x16x32_bf16 v[54:57], v[236:239], v[150:153], v[54:57]
	v_mfma_f32_16x16x32_bf16 v[50:53], v[244:247], v[150:153], v[50:53]
	v_mfma_f32_16x16x32_bf16 v[38:41], v[236:239], v[158:161], v[38:41]
	v_mfma_f32_16x16x32_bf16 v[34:37], v[244:247], v[158:161], v[34:37]
	v_mfma_f32_16x16x32_bf16 v[22:25], v[236:239], v[190:193], v[22:25]
	v_mfma_f32_16x16x32_bf16 v[18:21], v[244:247], v[190:193], v[18:21]
	v_mfma_f32_16x16x32_bf16 v[6:9], v[236:239], v[214:217], v[6:9]
	v_mfma_f32_16x16x32_bf16 v[2:5], v[244:247], v[214:217], v[2:5]
	s_setprio 0
	s_barrier
	s_add_u32 s20, s20, s60
	s_addc_u32 s21, s21, 0
	s_mov_b32 m0, s8
	v_lshl_add_u64 v[232:233], s[20:21], 0, v[168:169]
	s_add_i32 s24, 0, 0x18000
	v_add_u32_e32 v0, s24, v211
	global_load_lds_dwordx4 v[232:233], off
	v_lshl_add_u64 v[232:233], s[20:21], 0, v[172:173]
	s_mov_b32 m0, s9
	s_nop 0
	global_load_lds_dwordx4 v[232:233], off
	ds_read_b128 v[130:133], v0
	ds_read_b128 v[134:137], v0 offset:1024
	ds_read_b128 v[138:141], v0 offset:2048
	ds_read_b128 v[142:145], v0 offset:3072
	s_add_i32 s20, 0, 0x1c000
	s_add_i32 s21, s24, s30
	v_add_u32_e32 v0, s20, v211
	ds_read_b128 v[232:235], v0
	ds_read_b128 v[236:239], v0 offset:1024
	ds_read_b128 v[240:243], v0 offset:2048
	ds_read_b128 v[244:247], v0 offset:3072
	ds_read_b128 v[146:149], v212 offset:32768
	ds_read_b128 v[150:153], v212 offset:33792
	ds_read_b128 v[154:157], v212 offset:34816
	ds_read_b128 v[158:161], v212 offset:35840
	ds_read_b128 v[186:189], v212 offset:36864
	ds_read_b128 v[190:193], v212 offset:37888
	s_waitcnt lgkmcnt(12)
	ds_read_b128 v[194:197], v212 offset:38912
	ds_read_b128 v[214:217], v212 offset:39936
	s_waitcnt vmcnt(8) lgkmcnt(0)
	s_barrier
	s_setprio 1
	v_mfma_f32_16x16x32_bf16 v[126:129], v[130:133], v[146:149], v[126:129]
	v_mfma_f32_16x16x32_bf16 v[122:125], v[138:141], v[146:149], v[122:125]
	v_mfma_f32_16x16x32_bf16 v[110:113], v[130:133], v[154:157], v[110:113]
	v_mfma_f32_16x16x32_bf16 v[106:109], v[138:141], v[154:157], v[106:109]
	v_mfma_f32_16x16x32_bf16 v[94:97], v[130:133], v[186:189], v[94:97]
	v_mfma_f32_16x16x32_bf16 v[90:93], v[138:141], v[186:189], v[90:93]
	v_mfma_f32_16x16x32_bf16 v[78:81], v[130:133], v[194:197], v[78:81]
	v_mfma_f32_16x16x32_bf16 v[74:77], v[138:141], v[194:197], v[74:77]
	v_mfma_f32_16x16x32_bf16 v[126:129], v[134:137], v[150:153], v[126:129]
	v_mfma_f32_16x16x32_bf16 v[122:125], v[142:145], v[150:153], v[122:125]
	v_mfma_f32_16x16x32_bf16 v[110:113], v[134:137], v[158:161], v[110:113]
	v_mfma_f32_16x16x32_bf16 v[106:109], v[142:145], v[158:161], v[106:109]
	v_mfma_f32_16x16x32_bf16 v[94:97], v[134:137], v[190:193], v[94:97]
	v_mfma_f32_16x16x32_bf16 v[90:93], v[142:145], v[190:193], v[90:93]
	v_mfma_f32_16x16x32_bf16 v[78:81], v[134:137], v[214:217], v[78:81]
	v_mfma_f32_16x16x32_bf16 v[74:77], v[142:145], v[214:217], v[74:77]
	v_mfma_f32_16x16x32_bf16 v[118:121], v[232:235], v[146:149], v[118:121]
	v_mfma_f32_16x16x32_bf16 v[114:117], v[240:243], v[146:149], v[114:117]
	v_mfma_f32_16x16x32_bf16 v[102:105], v[232:235], v[154:157], v[102:105]
	v_mfma_f32_16x16x32_bf16 v[98:101], v[240:243], v[154:157], v[98:101]
	v_mfma_f32_16x16x32_bf16 v[86:89], v[232:235], v[186:189], v[86:89]
	v_mfma_f32_16x16x32_bf16 v[82:85], v[240:243], v[186:189], v[82:85]
	v_mfma_f32_16x16x32_bf16 v[70:73], v[232:235], v[194:197], v[70:73]
	v_mfma_f32_16x16x32_bf16 v[66:69], v[240:243], v[194:197], v[66:69]
	v_mfma_f32_16x16x32_bf16 v[118:121], v[236:239], v[150:153], v[118:121]
	v_mfma_f32_16x16x32_bf16 v[114:117], v[244:247], v[150:153], v[114:117]
	v_mfma_f32_16x16x32_bf16 v[102:105], v[236:239], v[158:161], v[102:105]
	v_mfma_f32_16x16x32_bf16 v[98:101], v[244:247], v[158:161], v[98:101]
	v_mfma_f32_16x16x32_bf16 v[86:89], v[236:239], v[190:193], v[86:89]
	v_mfma_f32_16x16x32_bf16 v[82:85], v[244:247], v[190:193], v[82:85]
	v_mfma_f32_16x16x32_bf16 v[70:73], v[236:239], v[214:217], v[70:73]
	v_mfma_f32_16x16x32_bf16 v[66:69], v[244:247], v[214:217], v[66:69]
	s_setprio 0
	s_barrier
	ds_read_b128 v[146:149], v212 offset:49152
	ds_read_b128 v[150:153], v212 offset:50176
	ds_read_b128 v[154:157], v212 offset:51200
	ds_read_b128 v[158:161], v212 offset:52224
	ds_read_b128 v[186:189], v212 offset:53248
	ds_read_b128 v[190:193], v212 offset:54272
	ds_read_b128 v[194:197], v212 offset:55296
	ds_read_b128 v[214:217], v212 offset:56320
	v_lshl_add_u64 v[198:199], v[198:199], 0, s[16:17]
	s_mov_b32 m0, s21
	v_lshl_add_u64 v[218:219], v[218:219], 0, s[16:17]
	global_load_lds_dwordx4 v[198:199], off
	s_add_i32 m0, s21, 0x2000
	s_nop 0
	global_load_lds_dwordx4 v[218:219], off
	s_mov_b32 m0, s97
	v_lshl_add_u64 v[248:249], v[248:249], 0, s[16:17]
	v_lshl_add_u64 v[250:251], v[250:251], 0, s[16:17]
	global_load_lds_dwordx4 v[248:249], off
	s_mov_b32 m0, s90
	s_nop 0
	global_load_lds_dwordx4 v[250:251], off
	s_add_i32 s20, s20, s30
	v_lshl_add_u64 v[226:227], v[226:227], 0, s[16:17]
	s_mov_b32 m0, s20
	v_lshl_add_u64 v[228:229], v[228:229], 0, s[16:17]
	global_load_lds_dwordx4 v[226:227], off
	s_add_i32 m0, s20, 0x2000
	s_nop 0
	global_load_lds_dwordx4 v[228:229], off
	s_waitcnt vmcnt(8) lgkmcnt(0)
	s_barrier
	s_setprio 1
	v_mfma_f32_16x16x32_bf16 v[62:65], v[130:133], v[146:149], v[62:65]
	v_mfma_f32_16x16x32_bf16 v[58:61], v[138:141], v[146:149], v[58:61]
	v_mfma_f32_16x16x32_bf16 v[46:49], v[130:133], v[154:157], v[46:49]
	v_mfma_f32_16x16x32_bf16 v[42:45], v[138:141], v[154:157], v[42:45]
	v_mfma_f32_16x16x32_bf16 v[30:33], v[130:133], v[186:189], v[30:33]
	v_mfma_f32_16x16x32_bf16 v[26:29], v[138:141], v[186:189], v[26:29]
	v_mfma_f32_16x16x32_bf16 v[14:17], v[130:133], v[194:197], v[14:17]
	v_mfma_f32_16x16x32_bf16 v[10:13], v[138:141], v[194:197], v[10:13]
	v_mfma_f32_16x16x32_bf16 v[62:65], v[134:137], v[150:153], v[62:65]
	v_mfma_f32_16x16x32_bf16 v[58:61], v[142:145], v[150:153], v[58:61]
	v_mfma_f32_16x16x32_bf16 v[46:49], v[134:137], v[158:161], v[46:49]
	v_mfma_f32_16x16x32_bf16 v[42:45], v[142:145], v[158:161], v[42:45]
	v_mfma_f32_16x16x32_bf16 v[30:33], v[134:137], v[190:193], v[30:33]
	v_mfma_f32_16x16x32_bf16 v[26:29], v[142:145], v[190:193], v[26:29]
	v_mfma_f32_16x16x32_bf16 v[14:17], v[134:137], v[214:217], v[14:17]
	v_mfma_f32_16x16x32_bf16 v[10:13], v[142:145], v[214:217], v[10:13]
	v_mfma_f32_16x16x32_bf16 v[54:57], v[232:235], v[146:149], v[54:57]
	v_mfma_f32_16x16x32_bf16 v[50:53], v[240:243], v[146:149], v[50:53]
	v_mfma_f32_16x16x32_bf16 v[38:41], v[232:235], v[154:157], v[38:41]
	v_mfma_f32_16x16x32_bf16 v[34:37], v[240:243], v[154:157], v[34:37]
	v_mfma_f32_16x16x32_bf16 v[22:25], v[232:235], v[186:189], v[22:25]
	v_mfma_f32_16x16x32_bf16 v[18:21], v[240:243], v[186:189], v[18:21]
	v_mfma_f32_16x16x32_bf16 v[6:9], v[232:235], v[194:197], v[6:9]
	v_mfma_f32_16x16x32_bf16 v[2:5], v[240:243], v[194:197], v[2:5]
	v_mfma_f32_16x16x32_bf16 v[54:57], v[236:239], v[150:153], v[54:57]
	v_mfma_f32_16x16x32_bf16 v[50:53], v[244:247], v[150:153], v[50:53]
	v_mfma_f32_16x16x32_bf16 v[38:41], v[236:239], v[158:161], v[38:41]
	v_mfma_f32_16x16x32_bf16 v[34:37], v[244:247], v[158:161], v[34:37]
	v_mfma_f32_16x16x32_bf16 v[22:25], v[236:239], v[190:193], v[22:25]
	v_mfma_f32_16x16x32_bf16 v[18:21], v[244:247], v[190:193], v[18:21]
	v_mfma_f32_16x16x32_bf16 v[6:9], v[236:239], v[214:217], v[6:9]
	v_mfma_f32_16x16x32_bf16 v[2:5], v[244:247], v[214:217], v[2:5]
	s_setprio 0
	s_add_u32 s38, s38, 0x100
	s_addc_u32 s39, s39, 0
	s_add_u32 s18, s18, 0x100
	s_addc_u32 s19, s19, 0
	s_cmp_ge_u32 s42, s91
	s_mov_b32 s20, s42
	s_barrier
	s_cbranch_scc0 .LBB0_919
	s_lshl_b32 s6, s6, 8
	s_and_b32 s6, s6, 0x7f00
	v_add_u32_e32 v186, s6, v210
	s_mov_b64 s[18:19], -1
	s_mov_b64 s[20:21], 0
	s_cmp_lt_i32 s96, 5
	s_mov_b64 s[38:39], 0
	s_cbranch_scc1 .LBB0_1060
	s_cmp_gt_i32 s96, 6
	s_cbranch_scc0 .LBB0_1056
	s_cmp_gt_i32 s96, 7
	s_cbranch_scc0 .LBB0_990
	s_cmp_eq_u32 s96, 8
	s_mov_b64 s[38:39], -1
	s_cbranch_scc0 .LBB0_989
	s_lshl_b32 s18, s5, 8
	s_ashr_i32 s19, s18, 31
	v_ashrrev_i32_e32 v187, 31, v186
	v_mov_b32_e32 v189, s19
	v_or_b32_e32 v188, s18, v162
	v_lshlrev_b64 v[192:193], 10, v[186:187]
	v_lshl_add_u64 v[130:131], v[192:193], 0, v[188:189]
	v_lshlrev_b64 v[130:131], 1, v[130:131]
	v_lshl_add_u64 v[132:133], s[0:1], 0, v[130:131]
	global_load_dwordx4 v[154:157], v[132:133], off
	v_lshl_add_u64 v[132:133], s[54:55], 0, v[130:131]
	v_or_b32_e32 v130, 0x100, v130
	v_lshl_add_u64 v[130:131], s[0:1], 0, v[130:131]
	global_load_dwordx4 v[158:161], v[132:133], off
	global_load_dwordx4 v[146:149], v[130:131], off
	global_load_dwordx4 v[150:153], v[132:133], off offset:256
	v_or_b32_e32 v130, 16, v186
	v_ashrrev_i32_e32 v131, 31, v130
	v_lshlrev_b64 v[190:191], 10, v[130:131]
	v_lshl_add_u64 v[130:131], v[190:191], 0, v[188:189]
	v_lshlrev_b64 v[130:131], 1, v[130:131]
	v_lshl_add_u64 v[132:133], s[0:1], 0, v[130:131]
	v_lshl_add_u64 v[134:135], s[54:55], 0, v[130:131]
	v_or_b32_e32 v130, 0x100, v130
	v_lshl_add_u64 v[130:131], s[0:1], 0, v[130:131]
	global_load_dwordx4 v[138:141], v[132:133], off
	global_load_dwordx4 v[142:145], v[134:135], off
	s_nop 0
	global_load_dwordx4 v[130:133], v[130:131], off
	s_nop 0
	global_load_dwordx4 v[134:137], v[134:135], off offset:256
	v_lshl_add_u64 v[194:195], v[192:193], 0, s[18:19]
	v_or_b32_e32 v194, v194, v162
	v_cndmask_b32_e64 v0, 0, 1, s[68:69]
	v_cmp_ne_u32_e64 s[42:43], 1, v0
	s_andn2_b64 vcc, exec, s[68:69]
	s_waitcnt vmcnt(0)
	v_lshlrev_b32_e32 v214, 16, v154
	v_and_b32_e32 v215, 0xffff0000, v154
	v_lshlrev_b32_e32 v154, 16, v155
	v_and_b32_e32 v155, 0xffff0000, v155
	v_lshlrev_b32_e32 v192, 16, v158
	v_and_b32_e32 v193, 0xffff0000, v158
	v_lshlrev_b32_e32 v158, 16, v159
	v_and_b32_e32 v159, 0xffff0000, v159
	v_lshlrev_b32_e32 v196, 16, v160
	v_and_b32_e32 v197, 0xffff0000, v160
	v_lshlrev_b32_e32 v198, 16, v161
	v_and_b32_e32 v199, 0xffff0000, v161
	v_lshlrev_b32_e32 v216, 16, v156
	v_and_b32_e32 v217, 0xffff0000, v156
	v_lshlrev_b32_e32 v156, 16, v157
	v_and_b32_e32 v157, 0xffff0000, v157
	v_pk_fma_f32 v[160:161], v[128:129], v[158:159], v[154:155]
	v_pk_fma_f32 v[158:159], v[126:127], v[192:193], v[214:215]
	v_pk_fma_f32 v[156:157], v[124:125], v[198:199], v[156:157]
	v_pk_fma_f32 v[154:155], v[122:123], v[196:197], v[216:217]
	v_lshl_add_u64 v[192:193], v[194:195], 2, s[12:13]
	v_lshl_add_u64 v[194:195], v[194:195], 1, s[48:49]
	global_store_dwordx4 v[192:193], v[158:161], off
	global_store_dwordx4 v[192:193], v[154:157], off offset:16
	s_cbranch_vccnz .LBB0_926
	v_cvt_pk_bf16_f32 v196, v158, v159
	v_cvt_pk_bf16_f32 v197, v160, v161
	v_cvt_pk_bf16_f32 v198, v154, v155
	v_cvt_pk_bf16_f32 v199, v156, v157
	global_store_dwordx4 v[194:195], v[196:199], off
